# mixer B: bias lookup via 32-float-pitch table with mask column and pre-rewritten column codes (bfe+addr+ds_read+fmac per score)
# speedup vs baseline: 1.0197x; 1.0028x over previous
;     __device__ __forceinline__ void init(int c, int hi) {
;         int cs = c - 8; cs = cs < 0 ? 0 : (cs > 48 ? 48 : cs);
;         unsigned wa[4] = {0u, 0u, 0u, 0u}, wb[4] = {0u, 0u, 0u, 0u};
; #pragma unroll
;         for (int ri = 0; ri < 16; ++ri) { const int kc0 = 16 * (ri >> 3) + 8 * hi + 4 * ((ri >> 2) & 1) + (ri & 3), kc1 = kc0 + 32;
;             int d0 = kc0 - c + 15; d0 = d0 < 0 ? 0 : (d0 > 30 ? 30 : d0); int d1 = kc1 - c + 15; d1 = d1 < 0 ? 0 : (d1 > 30 ? 30 : d1);
;             const unsigned e0 = (kc0 >= cs && kc0 < cs + 16) ? (unsigned)d0 : 0x80u, e1 = (kc1 >= cs && kc1 < cs + 16) ? (unsigned)d1 : 0x80u;
;             wa[ri >> 2] |= e0 << (8 * (ri & 3)); wb[ri >> 2] |= e1 << (8 * (ri & 3)); }
;         a0 = wa[0]; a1 = wa[1]; a2 = wa[2]; a3 = wa[3]; b0 = wb[0]; b1 = wb[1]; b2 = wb[2]; b3 = wb[3]; }
.LBB0_638:
	v_and_b32_e32 v3, 31, v0
	v_readlane_b32 s4, v255, 13
	v_ashrrev_i32_e32 v6, 2, v0
	s_add_u32 s12, s10, 0x10e00000
	v_or_b32_e32 v2, s4, v3
	v_med3_u32 v4, v2, 8, 56
	v_and_b32_e32 v68, -8, v6
	s_addc_u32 s13, s23, 0
	v_add_u32_e32 v5, -8, v4
	v_add_u32_e32 v7, 8, v4
	v_sub_u32_e32 v10, v68, v2
	s_add_u32 s16, s10, 0x6e00000
	v_add_u32_e32 v8, 32, v68
	v_med3_i32 v10, v10, -15, 15
	v_cmp_lt_i32_e32 vcc, v68, v7
	v_cmp_ge_i32_e64 s[4:5], v68, v5
	s_addc_u32 s18, s23, 0
	v_subrev_u32_e32 v4, 24, v4
	v_sub_u32_e32 v9, v8, v2
	v_add_u32_e32 v10, 15, v10
	s_and_b64 vcc, s[4:5], vcc
	v_med3_i32 v9, v9, -15, 15
	v_cndmask_b32_e32 v10, v205, v10, vcc
	v_cmp_lt_i32_e32 vcc, v68, v4
	v_cmp_ge_i32_e64 s[4:5], v8, v5
	v_add_u32_e32 v9, 15, v9
	s_and_b64 vcc, s[4:5], vcc
	v_cndmask_b32_e32 v8, v205, v9, vcc
	v_or_b32_e32 v9, 1, v68
	v_sub_u32_e32 v13, v9, v2
	v_add_u32_e32 v11, 33, v68
	v_med3_i32 v13, v13, -15, 15
	v_cmp_lt_i32_e32 vcc, v9, v7
	v_cmp_ge_i32_e64 s[6:7], v9, v5
	v_sub_u32_e32 v12, v11, v2
	v_lshl_add_u32 v13, v13, 8, v254
	s_and_b64 vcc, s[6:7], vcc
	v_med3_i32 v12, v12, -15, 15
	v_cmp_lt_i32_e64 s[4:5], v9, v4
	v_cndmask_b32_e32 v9, v200, v13, vcc
	v_cmp_ge_i32_e32 vcc, v11, v5
	v_or_b32_e32 v9, v9, v10
	v_lshl_add_u32 v10, v12, 8, v254
	s_and_b64 vcc, vcc, s[4:5]
	v_cndmask_b32_e32 v10, v200, v10, vcc
	v_or_b32_e32 v8, v10, v8
	v_or_b32_e32 v10, 2, v68
	v_sub_u32_e32 v13, v10, v2
	v_add_u32_e32 v11, 34, v68
	v_med3_i32 v13, v13, -15, 15
	v_cmp_lt_i32_e32 vcc, v10, v7
	v_cmp_ge_i32_e64 s[6:7], v10, v5
	v_sub_u32_e32 v12, v11, v2
	v_lshl_add_u32 v13, v13, 16, v208
	s_and_b64 vcc, s[6:7], vcc
	v_med3_i32 v12, v12, -15, 15
	v_cmp_lt_i32_e64 s[4:5], v10, v4
	v_cndmask_b32_e32 v10, v209, v13, vcc
	v_cmp_ge_i32_e32 vcc, v11, v5
	v_lshl_add_u32 v12, v12, 16, v208
	s_and_b64 vcc, vcc, s[4:5]
	v_cndmask_b32_e32 v11, v209, v12, vcc
	v_or_b32_e32 v12, 3, v68
	v_sub_u32_e32 v15, v12, v2
	v_add_u32_e32 v13, 35, v68
	v_med3_i32 v15, v15, -15, 15
	v_cmp_lt_i32_e32 vcc, v12, v7
	v_cmp_ge_i32_e64 s[6:7], v12, v5
	v_sub_u32_e32 v14, v13, v2
	v_lshl_add_u32 v15, v15, 24, v210
	s_and_b64 vcc, s[6:7], vcc
	v_med3_i32 v14, v14, -15, 15
	v_cmp_lt_i32_e64 s[4:5], v12, v4
	v_cndmask_b32_e32 v12, v211, v15, vcc
	v_cmp_ge_i32_e32 vcc, v13, v5
	v_or3_b32 v81, v9, v10, v12
	v_lshl_add_u32 v9, v14, 24, v210
	s_and_b64 vcc, vcc, s[4:5]
	v_cndmask_b32_e32 v9, v211, v9, vcc
	v_or3_b32 v82, v8, v11, v9
	v_or_b32_e32 v8, 4, v68
	v_sub_u32_e32 v11, v8, v2
	v_add_u32_e32 v9, 36, v68
	v_med3_i32 v11, v11, -15, 15
	v_cmp_lt_i32_e32 vcc, v8, v7
	v_cmp_ge_i32_e64 s[4:5], v8, v5
	v_sub_u32_e32 v10, v9, v2
	v_add_u32_e32 v11, 15, v11
	s_and_b64 vcc, s[4:5], vcc
	v_med3_i32 v10, v10, -15, 15
	v_cndmask_b32_e32 v11, v205, v11, vcc
	v_cmp_lt_i32_e32 vcc, v8, v4
	v_cmp_ge_i32_e64 s[4:5], v9, v5
	v_or_b32_e32 v9, 5, v68
	v_add_u32_e32 v10, 15, v10
	s_and_b64 vcc, s[4:5], vcc
	v_sub_u32_e32 v13, v9, v2
	v_cndmask_b32_e32 v8, v205, v10, vcc
	v_add_u32_e32 v10, 37, v68
	v_med3_i32 v13, v13, -15, 15
	v_cmp_lt_i32_e32 vcc, v9, v7
	v_cmp_ge_i32_e64 s[6:7], v9, v5
	v_sub_u32_e32 v12, v10, v2
	v_lshl_add_u32 v13, v13, 8, v254
	s_and_b64 vcc, s[6:7], vcc
	v_med3_i32 v12, v12, -15, 15
	v_cmp_lt_i32_e64 s[4:5], v9, v4
	v_cndmask_b32_e32 v9, v200, v13, vcc
	v_cmp_ge_i32_e32 vcc, v10, v5
	v_lshl_add_u32 v12, v12, 8, v254
	s_and_b64 vcc, vcc, s[4:5]
	v_cndmask_b32_e32 v10, v200, v12, vcc
	v_or_b32_e32 v8, v10, v8
	v_or_b32_e32 v10, 6, v68
	v_sub_u32_e32 v14, v10, v2
	v_add_u32_e32 v12, 38, v68
	v_med3_i32 v14, v14, -15, 15
	v_cmp_lt_i32_e32 vcc, v10, v7
	v_cmp_ge_i32_e64 s[6:7], v10, v5
	v_sub_u32_e32 v13, v12, v2
	v_lshl_add_u32 v14, v14, 16, v208
	s_and_b64 vcc, s[6:7], vcc
	v_med3_i32 v13, v13, -15, 15
	v_cmp_lt_i32_e64 s[4:5], v10, v4
	v_cndmask_b32_e32 v10, v209, v14, vcc
	v_cmp_ge_i32_e32 vcc, v12, v5
	v_or_b32_e32 v6, 7, v6
	v_lshl_add_u32 v13, v13, 16, v208
	s_and_b64 vcc, vcc, s[4:5]
	v_sub_u32_e32 v15, v6, v2
	v_cndmask_b32_e32 v12, v209, v13, vcc
	v_med3_i32 v15, v15, -15, 15
	v_cmp_lt_i32_e32 vcc, v6, v7
	v_cmp_ge_i32_e64 s[6:7], v6, v5
	v_add_u32_e32 v13, 39, v68
	v_lshl_add_u32 v15, v15, 24, v210
	s_and_b64 vcc, s[6:7], vcc
	v_sub_u32_e32 v14, v13, v2
	v_cmp_lt_i32_e64 s[4:5], v6, v4
	v_cndmask_b32_e32 v6, v211, v15, vcc
	v_med3_i32 v14, v14, -15, 15
	v_or_b32_e32 v6, v6, v11
	v_cmp_ge_i32_e32 vcc, v13, v5
	v_or3_b32 v83, v6, v9, v10
	v_lshl_add_u32 v6, v14, 24, v210
	s_and_b64 vcc, vcc, s[4:5]
	v_cndmask_b32_e32 v6, v211, v6, vcc
	v_or3_b32 v84, v8, v12, v6
	v_add_u32_e32 v6, 16, v68
	v_sub_u32_e32 v10, v6, v2
	v_add_u32_e32 v8, 48, v68
	v_med3_i32 v10, v10, -15, 15
	v_cmp_lt_i32_e32 vcc, v6, v7
	v_cmp_ge_i32_e64 s[4:5], v6, v5
	v_sub_u32_e32 v9, v8, v2
	v_add_u32_e32 v10, 15, v10
	s_and_b64 vcc, s[4:5], vcc
	v_med3_i32 v9, v9, -15, 15
	v_cndmask_b32_e32 v10, v205, v10, vcc
	v_cmp_lt_i32_e32 vcc, v6, v4
	v_cmp_ge_i32_e64 s[4:5], v8, v5
	v_add_u32_e32 v8, 17, v68
	v_add_u32_e32 v9, 15, v9
	s_and_b64 vcc, s[4:5], vcc
	v_sub_u32_e32 v12, v8, v2
	v_cndmask_b32_e32 v6, v205, v9, vcc
	v_add_u32_e32 v9, 49, v68
	v_med3_i32 v12, v12, -15, 15
	v_cmp_lt_i32_e32 vcc, v8, v7
	v_cmp_ge_i32_e64 s[6:7], v8, v5
	v_sub_u32_e32 v11, v9, v2
	v_lshl_add_u32 v12, v12, 8, v254
	s_and_b64 vcc, s[6:7], vcc
	v_med3_i32 v11, v11, -15, 15
	v_cmp_lt_i32_e64 s[4:5], v8, v4
	v_cndmask_b32_e32 v8, v200, v12, vcc
	v_cmp_ge_i32_e32 vcc, v9, v5
	v_or_b32_e32 v8, v8, v10
	v_lshl_add_u32 v10, v11, 8, v254
	s_and_b64 vcc, vcc, s[4:5]
	v_cndmask_b32_e32 v9, v200, v10, vcc
	v_or_b32_e32 v6, v9, v6
	v_add_u32_e32 v9, 18, v68
	v_sub_u32_e32 v12, v9, v2
	v_add_u32_e32 v10, 50, v68
	v_med3_i32 v12, v12, -15, 15
; #define LAS __attribute__((address_space(3)))
;     __device__ __forceinline__ const float* in(int i) const { return (const float*)(__attribute__((address_space(1))) const float*)ld64(i); }
;     __device__ __forceinline__ void init(int c, int hi) {
;         int cs = c - 8; cs = cs < 0 ? 0 : (cs > 48 ? 48 : cs);
;         unsigned wa[4] = {0u, 0u, 0u, 0u}, wb[4] = {0u, 0u, 0u, 0u};
; #pragma unroll
;         for (int ri = 0; ri < 16; ++ri) { const int kc0 = 16 * (ri >> 3) + 8 * hi + 4 * ((ri >> 2) & 1) + (ri & 3), kc1 = kc0 + 32;
;             int d0 = kc0 - c + 15; d0 = d0 < 0 ? 0 : (d0 > 30 ? 30 : d0); int d1 = kc1 - c + 15; d1 = d1 < 0 ? 0 : (d1 > 30 ? 30 : d1);
;             const unsigned e0 = (kc0 >= cs && kc0 < cs + 16) ? (unsigned)d0 : 0x80u, e1 = (kc1 >= cs && kc1 < cs + 16) ? (unsigned)d1 : 0x80u;
;             wa[ri >> 2] |= e0 << (8 * (ri & 3)); wb[ri >> 2] |= e1 << (8 * (ri & 3)); }
;         a0 = wa[0]; a1 = wa[1]; a2 = wa[2]; a3 = wa[3]; b0 = wb[0]; b1 = wb[1]; b2 = wb[2]; b3 = wb[3]; }
; __device__ __forceinline__ void attn_B2(const Ctx& a, LAS unsigned char* lds, int wave_s) {
;     ...
;         LAS float* tabl = (LAS float*)(lds + 24576);
;         { const float* tg = a.in(17) + h * 15 * 31; if (tid < 465) tabl[tid] = tg[tid] * LOG2E; }
;         f32x16 o[2]; float m, l; BiasNbrP bf; bf.r = r; bf.tab = tabl; bf.init(half * 32 + (lane & 31), lane >> 5);
	v_cmp_lt_i32_e32 vcc, v9, v7
	v_cmp_ge_i32_e64 s[6:7], v9, v5
	v_sub_u32_e32 v11, v10, v2
	v_lshl_add_u32 v12, v12, 16, v208
	s_and_b64 vcc, s[6:7], vcc
	v_med3_i32 v11, v11, -15, 15
	v_cmp_lt_i32_e64 s[4:5], v9, v4
	v_cndmask_b32_e32 v9, v209, v12, vcc
	v_cmp_ge_i32_e32 vcc, v10, v5
	v_lshl_add_u32 v11, v11, 16, v208
	s_and_b64 vcc, vcc, s[4:5]
	v_cndmask_b32_e32 v10, v209, v11, vcc
	v_add_u32_e32 v11, 19, v68
	v_sub_u32_e32 v14, v11, v2
	v_add_u32_e32 v12, 51, v68
	v_med3_i32 v14, v14, -15, 15
	v_cmp_lt_i32_e32 vcc, v11, v7
	v_cmp_ge_i32_e64 s[6:7], v11, v5
	v_sub_u32_e32 v13, v12, v2
	v_lshl_add_u32 v14, v14, 24, v210
	s_and_b64 vcc, s[6:7], vcc
	v_med3_i32 v13, v13, -15, 15
	v_cmp_lt_i32_e64 s[4:5], v11, v4
	v_cndmask_b32_e32 v11, v211, v14, vcc
	v_cmp_ge_i32_e32 vcc, v12, v5
	v_or3_b32 v85, v8, v9, v11
	v_lshl_add_u32 v8, v13, 24, v210
	s_and_b64 vcc, vcc, s[4:5]
	v_cndmask_b32_e32 v8, v211, v8, vcc
	v_or3_b32 v86, v6, v10, v8
	v_add_u32_e32 v6, 20, v68
	v_sub_u32_e32 v10, v6, v2
	v_add_u32_e32 v8, 52, v68
	v_med3_i32 v10, v10, -15, 15
	v_cmp_lt_i32_e32 vcc, v6, v7
	v_cmp_ge_i32_e64 s[4:5], v6, v5
	v_sub_u32_e32 v9, v8, v2
	v_add_u32_e32 v10, 15, v10
	s_and_b64 vcc, s[4:5], vcc
	v_med3_i32 v9, v9, -15, 15
	v_cndmask_b32_e32 v10, v205, v10, vcc
	v_cmp_lt_i32_e32 vcc, v6, v4
	v_cmp_ge_i32_e64 s[4:5], v8, v5
	v_add_u32_e32 v8, 21, v68
	v_add_u32_e32 v9, 15, v9
	s_and_b64 vcc, s[4:5], vcc
	v_sub_u32_e32 v12, v8, v2
	v_cndmask_b32_e32 v6, v205, v9, vcc
	v_add_u32_e32 v9, 53, v68
	v_med3_i32 v12, v12, -15, 15
	v_cmp_lt_i32_e32 vcc, v8, v7
	v_cmp_ge_i32_e64 s[6:7], v8, v5
	v_sub_u32_e32 v11, v9, v2
	v_lshl_add_u32 v12, v12, 8, v254
	s_and_b64 vcc, s[6:7], vcc
	v_med3_i32 v11, v11, -15, 15
	v_cmp_lt_i32_e64 s[4:5], v8, v4
	v_cndmask_b32_e32 v8, v200, v12, vcc
	v_cmp_ge_i32_e32 vcc, v9, v5
	v_or_b32_e32 v8, v8, v10
	v_lshl_add_u32 v10, v11, 8, v254
	s_and_b64 vcc, vcc, s[4:5]
	v_cndmask_b32_e32 v9, v200, v10, vcc
	v_or_b32_e32 v6, v9, v6
	v_add_u32_e32 v9, 22, v68
	v_sub_u32_e32 v12, v9, v2
	v_add_u32_e32 v10, 54, v68
	v_med3_i32 v12, v12, -15, 15
	v_cmp_lt_i32_e32 vcc, v9, v7
	v_cmp_ge_i32_e64 s[6:7], v9, v5
	v_sub_u32_e32 v11, v10, v2
	v_lshl_add_u32 v12, v12, 16, v208
	s_and_b64 vcc, s[6:7], vcc
	v_med3_i32 v11, v11, -15, 15
	v_cmp_lt_i32_e64 s[4:5], v9, v4
	v_cndmask_b32_e32 v9, v209, v12, vcc
	v_cmp_ge_i32_e32 vcc, v10, v5
	v_lshl_add_u32 v11, v11, 16, v208
	s_and_b64 vcc, vcc, s[4:5]
	v_cndmask_b32_e32 v10, v209, v11, vcc
	v_add_u32_e32 v11, 23, v68
	v_add_u32_e32 v12, 55, v68
	v_sub_u32_e32 v13, v12, v2
	v_sub_u32_e32 v2, v11, v2
	v_med3_i32 v2, v2, -15, 15
	v_cmp_lt_i32_e32 vcc, v11, v7
	v_cmp_ge_i32_e64 s[6:7], v11, v5
	v_lshl_add_u32 v2, v2, 24, v210
	s_and_b64 vcc, s[6:7], vcc
	v_cmp_lt_i32_e64 s[4:5], v11, v4
	v_cndmask_b32_e32 v2, v211, v2, vcc
	v_cmp_ge_i32_e32 vcc, v12, v5
	s_and_b64 vcc, vcc, s[4:5]
	v_readlane_b32 s4, v255, 14
	v_readlane_b32 s5, v255, 15
	s_lshl_b64 s[4:5], s[4:5], 1
	s_add_u32 s4, s10, s4
	s_addc_u32 s5, s23, s5
	s_add_u32 s6, s4, 0x1ae00000
	s_addc_u32 s7, s5, 0
	v_readlane_b32 s4, v255, 16
	v_readlane_b32 s5, v255, 17
	s_lshl_b64 s[4:5], s[4:5], 1
	s_add_u32 s4, s10, s4
	s_addc_u32 s5, s23, s5
	s_add_u32 s10, s4, 0x24e00000
	v_med3_i32 v13, v13, -15, 15
	s_addc_u32 s23, s5, 0
	v_or3_b32 v87, v8, v9, v2
	v_lshl_add_u32 v2, v13, 24, v210
	s_and_b64 s[4:5], s[14:15], exec
	v_readlane_b32 s0, v255, 1
	v_cndmask_b32_e32 v2, v211, v2, vcc
	v_lshlrev_b32_e32 v4, 3, v0
	s_cselect_b32 s4, s7, s23
	s_cselect_b32 s5, s6, s10
	v_add_u32_e32 v66, s0, v0
	v_or3_b32 v88, v6, v10, v2
	v_lshlrev_b32_e32 v2, 10, v0
	v_ashrrev_i32_e32 v5, 31, v4
	v_lshlrev_b32_e32 v6, 2, v0
	v_lshl_add_u32 v90, v0, 4, 0
	v_ashrrev_i32_e32 v0, 3, v0
	v_mov_b32_e32 v8, s5
	v_mov_b32_e32 v9, s4
	s_movk_i32 s0, 0x1d1
	v_and_b32_e32 v2, 0x7c00, v2
	v_xor_b32_e32 v89, 0x80, v6
	v_lshlrev_b32_e32 v6, 10, v3
	v_and_b32_e32 v70, -4, v0
	v_lshl_add_u64 v[72:73], v[4:5], 1, v[8:9]
	v_cmp_gt_i32_e64 s[0:1], s0, v66
	v_ashrrev_i32_e32 v67, 31, v66
	v_lshl_add_u32 v80, v66, 2, 0
	v_ashrrev_i32_e32 v69, 31, v68
	v_ashrrev_i32_e32 v71, 31, v70
	v_lshl_add_u64 v[74:75], v[72:73], 0, s[70:71]
	v_lshlrev_b32_e32 v0, 1, v2
	v_lshlrev_b32_e32 v76, 1, v6
	v_lshrrev_b32_e32 v222, 7, v81
	v_and_b32_e32 v222, 0x1010101, v222
	v_mul_lo_u32 v222, v222, 31
	v_and_b32_e32 v81, 0x1f1f1f1f, v81
	v_or_b32_e32 v81, v81, v222
	v_lshrrev_b32_e32 v222, 7, v82
	v_and_b32_e32 v222, 0x1010101, v222
	v_mul_lo_u32 v222, v222, 31
	v_and_b32_e32 v82, 0x1f1f1f1f, v82
	v_or_b32_e32 v82, v82, v222
	v_lshrrev_b32_e32 v222, 7, v83
	v_and_b32_e32 v222, 0x1010101, v222
	v_mul_lo_u32 v222, v222, 31
	v_and_b32_e32 v83, 0x1f1f1f1f, v83
	v_or_b32_e32 v83, v83, v222
	v_lshrrev_b32_e32 v222, 7, v84
	v_and_b32_e32 v222, 0x1010101, v222
	v_mul_lo_u32 v222, v222, 31
	v_and_b32_e32 v84, 0x1f1f1f1f, v84
	v_or_b32_e32 v84, v84, v222
	v_lshrrev_b32_e32 v222, 7, v85
	v_and_b32_e32 v222, 0x1010101, v222
	v_mul_lo_u32 v222, v222, 31
	v_and_b32_e32 v85, 0x1f1f1f1f, v85
	v_or_b32_e32 v85, v85, v222
	v_lshrrev_b32_e32 v222, 7, v86
	v_and_b32_e32 v222, 0x1010101, v222
	v_mul_lo_u32 v222, v222, 31
	v_and_b32_e32 v86, 0x1f1f1f1f, v86
	v_or_b32_e32 v86, v86, v222
	v_lshrrev_b32_e32 v222, 7, v87
	v_and_b32_e32 v222, 0x1010101, v222
	v_mul_lo_u32 v222, v222, 31
	v_and_b32_e32 v87, 0x1f1f1f1f, v87
	v_or_b32_e32 v87, v87, v222
	v_lshrrev_b32_e32 v222, 7, v88
	v_and_b32_e32 v222, 0x1010101, v222
	v_mul_lo_u32 v222, v222, 31
	v_and_b32_e32 v88, 0x1f1f1f1f, v88
	v_or_b32_e32 v88, v88, v222
	v_mul_u32_u24_e32 v243, 0x843, v66
	v_lshrrev_b32_e32 v243, 16, v243
	v_add_u32_e32 v242, v66, v243
	v_lshlrev_b32_e32 v242, 2, v242
	v_lshlrev_b32_e32 v243, 7, v243
	v_add_u32_e32 v243, 0x7c, v243
	s_branch .LBB0_641

; #define LAS __attribute__((address_space(3)))
;     __device__ __forceinline__ const float* in(int i) const { return (const float*)(__attribute__((address_space(1))) const float*)ld64(i); }
; __device__ __forceinline__ void attn_B2(const Ctx& a, LAS unsigned char* lds, int wave_s) {
;     ...
;         LAS float* tabl = (LAS float*)(lds + 24576);
;         { const float* tg = a.in(17) + h * 15 * 31; if (tid < 465) tabl[tid] = tg[tid] * LOG2E; }
.LBB0_641:
	v_readlane_b32 s4, v255, 31
	s_bfe_u32 s23, s8, 0x40005
	s_nop 0
	v_mov_b32_e32 v2, s4
	ds_read_b64 v[2:3], v2
	s_waitcnt lgkmcnt(0)
	v_readfirstlane_b32 s6, v2
	v_readfirstlane_b32 s7, v3
	s_and_saveexec_b64 s[4:5], s[0:1]
	s_cbranch_execz .LBB0_643
	s_mul_i32 s10, s23, 0x744
	s_add_u32 s6, s6, s10
	s_addc_u32 s7, s7, 0
	v_lshl_add_u64 v[2:3], v[66:67], 2, s[6:7]
	global_load_dword v2, v[2:3], off
	s_waitcnt vmcnt(0)
	v_mul_f32_e32 v2, 0x3fb8aa3b, v2
	ds_write_b32 v242, v2 offset:24576
	ds_write_b32 v243, v203 offset:24576

; #define LAS __attribute__((address_space(3)))
; __device__ __forceinline__ float shx(float v, int mask, int lane) { return __builtin_bit_cast(float, __builtin_amdgcn_ds_bpermute((lane ^ mask) << 2, __builtin_bit_cast(int, v))); }
; template <class BiasF> ...
;     ...
;         if (kt >= klo && kt < khi) {
;             const LAS unsigned char* sb = lds + s * 8192 + lane * 16;
;             bf16x8 KF[4], VA[2][2];
; #pragma unroll
;             for (int d0 = 0; d0 < 4; ++d0) KF[d0] = *(const LAS bf16x8*)(sb + d0 * 1024);
; #pragma unroll
;             for (int i2 = 0; i2 < 2; ++i2) { VA[i2][0] = *(const LAS bf16x8*)(sb + 4096 + i2 * 1024); VA[i2][1] = *(const LAS bf16x8*)(sb + 4096 + (2 + i2) * 1024); }
;             f32x16 sc;
; #pragma unroll
;             for (int r = 0; r < 16; ++r) sc[r] = 0.f;
; #pragma unroll
;             for (int d0 = 0; d0 < 4; ++d0) sc = __builtin_amdgcn_mfma_f32_32x32x16_bf16(KF[d0], qr[d0], sc, 0, 0, 0);
;             const float ktf = (float)(kt + 8 * hi);
;             float tmax = -3.0e38f;
; #pragma unroll
;             for (int r = 0; r < 16; ++r) { sc[r] = sc[r] * c2 + bias.at(r32, kt, ktf + (float)(16 * (r >> 3) + 4 * ((r >> 2) & 1) + (r & 3)), r); tmax = fmaxf(tmax, sc[r]); }
;             tmax = fmaxf(tmax, shx(tmax, 32, lane));
;             if (__any(tmax > m)) { const float mn = fmaxf(m, tmax); const float alpha = __builtin_amdgcn_exp2f(m - mn); m = mn; l *= alpha;
; #pragma unroll
;                 for (int i2 = 0; i2 < 2; ++i2)
; #pragma unroll
;                     for (int r = 0; r < 16; ++r) o[i2][r] *= alpha; }
.LBB0_653:
	s_cmp_lt_i32 s31, s25
	s_cselect_b64 s[4:5], -1, 0
	s_cmp_ge_i32 s31, s29
	s_cselect_b64 s[38:39], -1, 0
	s_or_b64 s[4:5], s[4:5], s[38:39]
	s_and_b64 vcc, exec, s[4:5]
	s_cbranch_vccnz .LBB0_657
	v_lshl_add_u32 v108, s34, 13, v90
	ds_read_b128 v[34:37], v108
	ds_read_b128 v[92:95], v108 offset:1024
	ds_read_b128 v[96:99], v108 offset:2048
	ds_read_b128 v[100:103], v108 offset:3072
	s_add_i32 s4, s24, s36
	s_bitcmp0_b32 s36, 0
	s_cselect_b64 vcc, -1, 0
	s_lshr_b32 s4, s4, 1
	s_sub_i32 s4, s4, s28
	s_lshl_b32 s36, s4, 7
	v_cndmask_b32_e32 v222, v82, v81, vcc
	v_cndmask_b32_e32 v223, v84, v83, vcc
	v_cndmask_b32_e32 v224, v86, v85, vcc
	v_cndmask_b32_e32 v225, v88, v87, vcc
	s_waitcnt lgkmcnt(0)
	v_mfma_f32_32x32x16_bf16 v[34:49], v[34:37], v[50:53], 0
	v_bfe_u32 v226, v222, 0, 5
	v_lshl_add_u32 v226, v226, 2, s36
	v_bfe_u32 v227, v222, 8, 5
	v_lshl_add_u32 v227, v227, 2, s36
	v_bfe_u32 v228, v222, 16, 5
	v_lshl_add_u32 v228, v228, 2, s36
	v_bfe_u32 v229, v222, 24, 5
	v_lshl_add_u32 v229, v229, 2, s36
	v_mfma_f32_32x32x16_bf16 v[34:49], v[92:95], v[54:57], v[34:49]
	v_bfe_u32 v230, v223, 0, 5
	v_lshl_add_u32 v230, v230, 2, s36
	v_bfe_u32 v231, v223, 8, 5
	v_lshl_add_u32 v231, v231, 2, s36
	v_bfe_u32 v232, v223, 16, 5
	v_lshl_add_u32 v232, v232, 2, s36
	v_bfe_u32 v233, v223, 24, 5
	v_lshl_add_u32 v233, v233, 2, s36
	v_mfma_f32_32x32x16_bf16 v[34:49], v[96:99], v[58:61], v[34:49]
	v_bfe_u32 v234, v224, 0, 5
	v_lshl_add_u32 v234, v234, 2, s36
	v_bfe_u32 v235, v224, 8, 5
	v_lshl_add_u32 v235, v235, 2, s36
	v_bfe_u32 v236, v224, 16, 5
	v_lshl_add_u32 v236, v236, 2, s36
	v_bfe_u32 v237, v224, 24, 5
	v_lshl_add_u32 v237, v237, 2, s36
	v_mfma_f32_32x32x16_bf16 v[34:49], v[100:103], v[62:65], v[34:49]
	v_bfe_u32 v238, v225, 0, 5
	v_lshl_add_u32 v238, v238, 2, s36
	v_bfe_u32 v239, v225, 8, 5
	v_lshl_add_u32 v239, v239, 2, s36
	v_bfe_u32 v240, v225, 16, 5
	v_lshl_add_u32 v240, v240, 2, s36
	v_bfe_u32 v241, v225, 24, 5
	v_lshl_add_u32 v241, v241, 2, s36
	ds_read_b32 v99, v226 offset:25472
	ds_read_b32 v97, v227 offset:25472
	ds_read_b32 v98, v228 offset:25472
	ds_read_b32 v95, v229 offset:25472
	ds_read_b32 v96, v230 offset:25472
	ds_read_b32 v93, v231 offset:25472
	ds_read_b32 v94, v232 offset:25472
	ds_read_b32 v92, v233 offset:25472
	ds_read_b32 v107, v234 offset:25472
	ds_read_b32 v105, v235 offset:25472
	ds_read_b32 v106, v236 offset:25472
	ds_read_b32 v103, v237 offset:25472
	ds_read_b32 v104, v238 offset:25472
	ds_read_b32 v101, v239 offset:25472
	ds_read_b32 v102, v240 offset:25472
	ds_read_b32 v100, v241 offset:25472
	s_waitcnt lgkmcnt(0)
	v_fmac_f32_e32 v99, 0x3e38aa3b, v34
	v_fmac_f32_e32 v97, 0x3e38aa3b, v35
	v_fmac_f32_e32 v98, 0x3e38aa3b, v36
	v_fmac_f32_e32 v95, 0x3e38aa3b, v37
	v_fmac_f32_e32 v96, 0x3e38aa3b, v38
	v_fmac_f32_e32 v93, 0x3e38aa3b, v39
	v_fmac_f32_e32 v94, 0x3e38aa3b, v40
	v_fmac_f32_e32 v92, 0x3e38aa3b, v41
	v_fmac_f32_e32 v107, 0x3e38aa3b, v42
	v_fmac_f32_e32 v105, 0x3e38aa3b, v43
	v_fmac_f32_e32 v106, 0x3e38aa3b, v44
	v_fmac_f32_e32 v103, 0x3e38aa3b, v45
	v_fmac_f32_e32 v104, 0x3e38aa3b, v46
	v_fmac_f32_e32 v101, 0x3e38aa3b, v47
	v_fmac_f32_e32 v102, 0x3e38aa3b, v48
	v_fmac_f32_e32 v100, 0x3e38aa3b, v49
	v_max3_f32 v226, v99, s53, v97
	v_max3_f32 v226, v226, v98, v95
	v_max3_f32 v226, v226, v96, v93
	v_max3_f32 v226, v226, v94, v92
	v_max3_f32 v226, v226, v107, v105
	v_max3_f32 v226, v226, v106, v103
	v_max3_f32 v226, v226, v104, v101
	v_max3_f32 v109, v226, v102, v100
	v_mov_b32_e32 v110, v109
	ds_read_b128 v[46:49], v108 offset:4096
	ds_read_b128 v[38:41], v108 offset:5120
	ds_read_b128 v[42:45], v108 offset:6144
	ds_read_b128 v[34:37], v108 offset:7168
	v_permlane32_swap_b32_e32 v110, v109
	v_max_f32_e32 v108, v110, v110
	v_max_f32_e32 v108, v109, v108
	v_cmp_gt_f32_e32 vcc, v108, v91
	s_cbranch_vccz .LBB0_656
	v_max_f32_e32 v108, v108, v108
	v_max_f32_e32 v109, v91, v91
	v_max_f32_e32 v109, v109, v108
	v_sub_f32_e32 v91, v91, v109
	v_exp_f32_e32 v108, v91
	v_mov_b32_e32 v91, v109
	v_pk_mul_f32 v[16:17], v[16:17], v[108:109] op_sel_hi:[1,0]
	v_pk_mul_f32 v[14:15], v[14:15], v[108:109] op_sel_hi:[1,0]
	v_pk_mul_f32 v[12:13], v[12:13], v[108:109] op_sel_hi:[1,0]
	v_pk_mul_f32 v[10:11], v[10:11], v[108:109] op_sel_hi:[1,0]
	v_pk_mul_f32 v[8:9], v[8:9], v[108:109] op_sel_hi:[1,0]
	v_pk_mul_f32 v[6:7], v[6:7], v[108:109] op_sel_hi:[1,0]
	v_pk_mul_f32 v[4:5], v[4:5], v[108:109] op_sel_hi:[1,0]
	v_pk_mul_f32 v[2:3], v[2:3], v[108:109] op_sel_hi:[1,0]
	v_pk_mul_f32 v[32:33], v[32:33], v[108:109] op_sel_hi:[1,0]
	v_pk_mul_f32 v[30:31], v[30:31], v[108:109] op_sel_hi:[1,0]
	v_pk_mul_f32 v[28:29], v[28:29], v[108:109] op_sel_hi:[1,0]
	v_pk_mul_f32 v[26:27], v[26:27], v[108:109] op_sel_hi:[1,0]
	v_pk_mul_f32 v[24:25], v[24:25], v[108:109] op_sel_hi:[1,0]
	v_pk_mul_f32 v[22:23], v[22:23], v[108:109] op_sel_hi:[1,0]
	v_pk_mul_f32 v[20:21], v[20:21], v[108:109] op_sel_hi:[1,0]
	v_pk_mul_f32 v[18:19], v[18:19], v[108:109] op_sel_hi:[1,0]
	v_mul_f32_e32 v77, v77, v108
